# m2a: retention V^T transpose issues all 64 row loads up front; conv loop loads the next 8 tokens one iteration ahead (both were serialized load-wait chains)
# baseline (speedup 1.0000x reference)
; PH_FN ph_m2a(const Params& prm, unsigned char* lds, int l_) {
;     ...
;         {
;             const int c = 2 * C.tid, h = c >> 8, e = c & 255;
;             const bf16_t* __restrict__ src = PROJ + (size_t)tb * LDP + RV0 + c;
;             bf16_t* __restrict__ d0 = VTR + (size_t)(b * 4 + h) * 256 * SEQ + ((size_t)(sl0 >> 3) * 256 + (e >> 1)) * 8;
;             for (int t8 = 0; t8 < 8; ++t8) { unsigned u[8];
; #pragma unroll
;                 for (int ti = 0; ti < 8; ++ti) u[ti] = *(const unsigned*)(src + (size_t)(t8 * 8 + ti) * LDP);
;                 u32x4 lo, hi2;
;                 lo.x = (u[0] & 0xffffu) | (u[1] << 16); lo.y = (u[2] & 0xffffu) | (u[3] << 16); lo.z = (u[4] & 0xffffu) | (u[5] << 16); lo.w = (u[6] & 0xffffu) | (u[7] << 16);
;                 hi2.x = (u[0] >> 16) | (u[1] & 0xffff0000u); hi2.y = (u[2] >> 16) | (u[3] & 0xffff0000u); hi2.z = (u[4] >> 16) | (u[5] & 0xffff0000u); hi2.w = (u[6] >> 16) | (u[7] & 0xffff0000u);
;                 *(u32x4*)(d0 + (size_t)t8 * 256 * 8) = lo; *(u32x4*)(d0 + (size_t)t8 * 256 * 8 + 128 * 8) = hi2; }
.LBB0_286:
	s_or_b64 exec, exec, s[60:61]
	v_lshl_add_u32 v6, s97, 2, v59
	s_add_u32 s8, s28, s58
	v_ashrrev_i32_e32 v7, 31, v6
	s_addc_u32 s9, s29, s59
	v_lshlrev_b64 v[6:7], 21, v[6:7]
	v_lshl_add_u64 v[4:5], v[20:21], 1, s[8:9]
	v_lshl_add_u64 v[6:7], s[44:45], 0, v[6:7]
	v_lshlrev_b64 v[2:3], 12, v[2:3]
	v_lshl_add_u64 v[2:3], v[6:7], 0, v[2:3]
	v_add_co_u32_e32 v164, vcc, 0x3000, v4
	s_nop 1
	v_addc_co_u32_e32 v165, vcc, 0, v5, vcc
	global_load_dword v100, v[164:165], off
	v_add_co_u32_e32 v164, vcc, 0x7000, v4
	s_nop 1
	v_addc_co_u32_e32 v165, vcc, 0, v5, vcc
	global_load_dword v101, v[164:165], off
	v_add_co_u32_e32 v164, vcc, 0xb000, v4
	s_nop 1
	v_addc_co_u32_e32 v165, vcc, 0, v5, vcc
	global_load_dword v102, v[164:165], off
	v_add_co_u32_e32 v164, vcc, 0xf000, v4
	s_nop 1
	v_addc_co_u32_e32 v165, vcc, 0, v5, vcc
	global_load_dword v103, v[164:165], off
	v_add_co_u32_e32 v164, vcc, 0x13000, v4
	s_nop 1
	v_addc_co_u32_e32 v165, vcc, 0, v5, vcc
	global_load_dword v104, v[164:165], off
	v_add_co_u32_e32 v164, vcc, 0x17000, v4
	s_nop 1
	v_addc_co_u32_e32 v165, vcc, 0, v5, vcc
	global_load_dword v105, v[164:165], off
	v_add_co_u32_e32 v164, vcc, 0x1b000, v4
	s_nop 1
	v_addc_co_u32_e32 v165, vcc, 0, v5, vcc
	global_load_dword v106, v[164:165], off
	v_add_co_u32_e32 v164, vcc, 0x1f000, v4
	s_nop 1
	v_addc_co_u32_e32 v165, vcc, 0, v5, vcc
	global_load_dword v107, v[164:165], off
	v_add_co_u32_e32 v164, vcc, 0x23000, v4
	s_nop 1
	v_addc_co_u32_e32 v165, vcc, 0, v5, vcc
	global_load_dword v108, v[164:165], off
	v_add_co_u32_e32 v164, vcc, 0x27000, v4
	s_nop 1
	v_addc_co_u32_e32 v165, vcc, 0, v5, vcc
	global_load_dword v109, v[164:165], off
	v_add_co_u32_e32 v164, vcc, 0x2b000, v4
	s_nop 1
	v_addc_co_u32_e32 v165, vcc, 0, v5, vcc
	global_load_dword v110, v[164:165], off
	v_add_co_u32_e32 v164, vcc, 0x2f000, v4
	s_nop 1
	v_addc_co_u32_e32 v165, vcc, 0, v5, vcc
	global_load_dword v111, v[164:165], off
	v_add_co_u32_e32 v164, vcc, 0x33000, v4
	s_nop 1
	v_addc_co_u32_e32 v165, vcc, 0, v5, vcc
	global_load_dword v112, v[164:165], off
	v_add_co_u32_e32 v164, vcc, 0x37000, v4
	s_nop 1
	v_addc_co_u32_e32 v165, vcc, 0, v5, vcc
	global_load_dword v113, v[164:165], off
	v_add_co_u32_e32 v164, vcc, 0x3b000, v4
	s_nop 1
	v_addc_co_u32_e32 v165, vcc, 0, v5, vcc
	global_load_dword v114, v[164:165], off
	v_add_co_u32_e32 v164, vcc, 0x3f000, v4
	s_nop 1
	v_addc_co_u32_e32 v165, vcc, 0, v5, vcc
	global_load_dword v115, v[164:165], off
	v_add_co_u32_e32 v164, vcc, 0x43000, v4
	s_nop 1
	v_addc_co_u32_e32 v165, vcc, 0, v5, vcc
	global_load_dword v116, v[164:165], off
	v_add_co_u32_e32 v164, vcc, 0x47000, v4
	s_nop 1
	v_addc_co_u32_e32 v165, vcc, 0, v5, vcc
	global_load_dword v117, v[164:165], off
	v_add_co_u32_e32 v164, vcc, 0x4b000, v4
	s_nop 1
	v_addc_co_u32_e32 v165, vcc, 0, v5, vcc
	global_load_dword v118, v[164:165], off
	v_add_co_u32_e32 v164, vcc, 0x4f000, v4
	s_nop 1
	v_addc_co_u32_e32 v165, vcc, 0, v5, vcc
	global_load_dword v119, v[164:165], off
	v_add_co_u32_e32 v164, vcc, 0x53000, v4
	s_nop 1
	v_addc_co_u32_e32 v165, vcc, 0, v5, vcc
	global_load_dword v120, v[164:165], off
	v_add_co_u32_e32 v164, vcc, 0x57000, v4
	s_nop 1
	v_addc_co_u32_e32 v165, vcc, 0, v5, vcc
	global_load_dword v121, v[164:165], off
	v_add_co_u32_e32 v164, vcc, 0x5b000, v4
	s_nop 1
	v_addc_co_u32_e32 v165, vcc, 0, v5, vcc
	global_load_dword v122, v[164:165], off
	v_add_co_u32_e32 v164, vcc, 0x5f000, v4
	s_nop 1
	v_addc_co_u32_e32 v165, vcc, 0, v5, vcc
	global_load_dword v123, v[164:165], off
	v_add_co_u32_e32 v164, vcc, 0x63000, v4
	s_nop 1
	v_addc_co_u32_e32 v165, vcc, 0, v5, vcc
	global_load_dword v124, v[164:165], off
	v_add_co_u32_e32 v164, vcc, 0x67000, v4
	s_nop 1
	v_addc_co_u32_e32 v165, vcc, 0, v5, vcc
	global_load_dword v125, v[164:165], off
	v_add_co_u32_e32 v164, vcc, 0x6b000, v4
	s_nop 1
	v_addc_co_u32_e32 v165, vcc, 0, v5, vcc
	global_load_dword v126, v[164:165], off
	v_add_co_u32_e32 v164, vcc, 0x6f000, v4
	s_nop 1
	v_addc_co_u32_e32 v165, vcc, 0, v5, vcc
	global_load_dword v127, v[164:165], off
	v_add_co_u32_e32 v164, vcc, 0x73000, v4
	s_nop 1
	v_addc_co_u32_e32 v165, vcc, 0, v5, vcc
	global_load_dword v128, v[164:165], off
	v_add_co_u32_e32 v164, vcc, 0x77000, v4
	s_nop 1
	v_addc_co_u32_e32 v165, vcc, 0, v5, vcc
	global_load_dword v129, v[164:165], off
	v_add_co_u32_e32 v164, vcc, 0x7b000, v4
	s_nop 1
	v_addc_co_u32_e32 v165, vcc, 0, v5, vcc
	global_load_dword v130, v[164:165], off
	v_add_co_u32_e32 v164, vcc, 0x7f000, v4
	s_nop 1
	v_addc_co_u32_e32 v165, vcc, 0, v5, vcc
	global_load_dword v131, v[164:165], off
	v_add_co_u32_e32 v164, vcc, 0x83000, v4
	s_nop 1
	v_addc_co_u32_e32 v165, vcc, 0, v5, vcc
	global_load_dword v132, v[164:165], off
	v_add_co_u32_e32 v164, vcc, 0x87000, v4
	s_nop 1
	v_addc_co_u32_e32 v165, vcc, 0, v5, vcc
	global_load_dword v133, v[164:165], off
	v_add_co_u32_e32 v164, vcc, 0x8b000, v4
	s_nop 1
	v_addc_co_u32_e32 v165, vcc, 0, v5, vcc
	global_load_dword v134, v[164:165], off
	v_add_co_u32_e32 v164, vcc, 0x8f000, v4
	s_nop 1
	v_addc_co_u32_e32 v165, vcc, 0, v5, vcc
	global_load_dword v135, v[164:165], off
	v_add_co_u32_e32 v164, vcc, 0x93000, v4
	s_nop 1
	v_addc_co_u32_e32 v165, vcc, 0, v5, vcc
	global_load_dword v136, v[164:165], off
	v_add_co_u32_e32 v164, vcc, 0x97000, v4
	s_nop 1
	v_addc_co_u32_e32 v165, vcc, 0, v5, vcc
	global_load_dword v137, v[164:165], off
	v_add_co_u32_e32 v164, vcc, 0x9b000, v4
	s_nop 1
	v_addc_co_u32_e32 v165, vcc, 0, v5, vcc
	global_load_dword v138, v[164:165], off
	v_add_co_u32_e32 v164, vcc, 0x9f000, v4
	s_nop 1
	v_addc_co_u32_e32 v165, vcc, 0, v5, vcc
	global_load_dword v139, v[164:165], off
; PH_FN ph_m2a(const Params& prm, unsigned char* lds, int l_) {
;     ...
;             for (int t8 = 0; t8 < 8; ++t8) { unsigned u[8];
; #pragma unroll
;                 for (int ti = 0; ti < 8; ++ti) u[ti] = *(const unsigned*)(src + (size_t)(t8 * 8 + ti) * LDP);
;                 u32x4 lo, hi2;
;                 lo.x = (u[0] & 0xffffu) | (u[1] << 16); lo.y = (u[2] & 0xffffu) | (u[3] << 16); lo.z = (u[4] & 0xffffu) | (u[5] << 16); lo.w = (u[6] & 0xffffu) | (u[7] << 16);
;                 hi2.x = (u[0] >> 16) | (u[1] & 0xffff0000u); hi2.y = (u[2] >> 16) | (u[3] & 0xffff0000u); hi2.z = (u[4] >> 16) | (u[5] & 0xffff0000u); hi2.w = (u[6] >> 16) | (u[7] & 0xffff0000u);
;                 *(u32x4*)(d0 + (size_t)t8 * 256 * 8) = lo; *(u32x4*)(d0 + (size_t)t8 * 256 * 8 + 128 * 8) = hi2; }
	v_add_co_u32_e32 v164, vcc, 0xa3000, v4
	s_nop 1
	v_addc_co_u32_e32 v165, vcc, 0, v5, vcc
	global_load_dword v140, v[164:165], off
	v_add_co_u32_e32 v164, vcc, 0xa7000, v4
	s_nop 1
	v_addc_co_u32_e32 v165, vcc, 0, v5, vcc
	global_load_dword v141, v[164:165], off
	v_add_co_u32_e32 v164, vcc, 0xab000, v4
	s_nop 1
	v_addc_co_u32_e32 v165, vcc, 0, v5, vcc
	global_load_dword v142, v[164:165], off
	v_add_co_u32_e32 v164, vcc, 0xaf000, v4
	s_nop 1
	v_addc_co_u32_e32 v165, vcc, 0, v5, vcc
	global_load_dword v143, v[164:165], off
	v_add_co_u32_e32 v164, vcc, 0xb3000, v4
	s_nop 1
	v_addc_co_u32_e32 v165, vcc, 0, v5, vcc
	global_load_dword v144, v[164:165], off
	v_add_co_u32_e32 v164, vcc, 0xb7000, v4
	s_nop 1
	v_addc_co_u32_e32 v165, vcc, 0, v5, vcc
	global_load_dword v145, v[164:165], off
	v_add_co_u32_e32 v164, vcc, 0xbb000, v4
	s_nop 1
	v_addc_co_u32_e32 v165, vcc, 0, v5, vcc
	global_load_dword v146, v[164:165], off
	v_add_co_u32_e32 v164, vcc, 0xbf000, v4
	s_nop 1
	v_addc_co_u32_e32 v165, vcc, 0, v5, vcc
	global_load_dword v147, v[164:165], off
	v_add_co_u32_e32 v164, vcc, 0xc3000, v4
	s_nop 1
	v_addc_co_u32_e32 v165, vcc, 0, v5, vcc
	global_load_dword v148, v[164:165], off
	v_add_co_u32_e32 v164, vcc, 0xc7000, v4
	s_nop 1
	v_addc_co_u32_e32 v165, vcc, 0, v5, vcc
	global_load_dword v149, v[164:165], off
	v_add_co_u32_e32 v164, vcc, 0xcb000, v4
	s_nop 1
	v_addc_co_u32_e32 v165, vcc, 0, v5, vcc
	global_load_dword v150, v[164:165], off
	v_add_co_u32_e32 v164, vcc, 0xcf000, v4
	s_nop 1
	v_addc_co_u32_e32 v165, vcc, 0, v5, vcc
	global_load_dword v151, v[164:165], off
	v_add_co_u32_e32 v164, vcc, 0xd3000, v4
	s_nop 1
	v_addc_co_u32_e32 v165, vcc, 0, v5, vcc
	global_load_dword v152, v[164:165], off
	v_add_co_u32_e32 v164, vcc, 0xd7000, v4
	s_nop 1
	v_addc_co_u32_e32 v165, vcc, 0, v5, vcc
	global_load_dword v153, v[164:165], off
	v_add_co_u32_e32 v164, vcc, 0xdb000, v4
	s_nop 1
	v_addc_co_u32_e32 v165, vcc, 0, v5, vcc
	global_load_dword v154, v[164:165], off
	v_add_co_u32_e32 v164, vcc, 0xdf000, v4
	s_nop 1
	v_addc_co_u32_e32 v165, vcc, 0, v5, vcc
	global_load_dword v155, v[164:165], off
	v_add_co_u32_e32 v164, vcc, 0xe3000, v4
	s_nop 1
	v_addc_co_u32_e32 v165, vcc, 0, v5, vcc
	global_load_dword v156, v[164:165], off
	v_add_co_u32_e32 v164, vcc, 0xe7000, v4
	s_nop 1
	v_addc_co_u32_e32 v165, vcc, 0, v5, vcc
	global_load_dword v157, v[164:165], off
	v_add_co_u32_e32 v164, vcc, 0xeb000, v4
	s_nop 1
	v_addc_co_u32_e32 v165, vcc, 0, v5, vcc
	global_load_dword v158, v[164:165], off
	v_add_co_u32_e32 v164, vcc, 0xef000, v4
	s_nop 1
	v_addc_co_u32_e32 v165, vcc, 0, v5, vcc
	global_load_dword v159, v[164:165], off
	v_add_co_u32_e32 v164, vcc, 0xf3000, v4
	s_nop 1
	v_addc_co_u32_e32 v165, vcc, 0, v5, vcc
	global_load_dword v160, v[164:165], off
	v_add_co_u32_e32 v164, vcc, 0xf7000, v4
	s_nop 1
	v_addc_co_u32_e32 v165, vcc, 0, v5, vcc
	global_load_dword v161, v[164:165], off
	v_add_co_u32_e32 v164, vcc, 0xfb000, v4
	s_nop 1
	v_addc_co_u32_e32 v165, vcc, 0, v5, vcc
	global_load_dword v162, v[164:165], off
	v_add_co_u32_e32 v164, vcc, 0xff000, v4
	s_nop 1
	v_addc_co_u32_e32 v165, vcc, 0, v5, vcc
	global_load_dword v163, v[164:165], off
	v_add_co_u32_e32 v6, vcc, s37, v4
	s_movk_i32 s5, 0x7000
	s_nop 0
	v_addc_co_u32_e32 v7, vcc, 0, v5, vcc
	s_waitcnt vmcnt(56)
	v_mov_b32_e32 v0, v100
	v_add_co_u32_e32 v6, vcc, s5, v4
	v_mov_b32_e32 v11, v1
	s_nop 0
	v_addc_co_u32_e32 v7, vcc, 0, v5, vcc
	s_mov_b32 s5, 0xb000
	v_lshl_add_u64 v[2:3], v[2:3], 0, v[10:11]
	v_mov_b32_e32 v11, v101
	v_add_co_u32_e32 v6, vcc, s5, v4
	s_mov_b32 s5, 0xf000
	s_nop 0
	v_addc_co_u32_e32 v7, vcc, 0, v5, vcc
	v_mov_b32_e32 v13, v102
	v_add_co_u32_e32 v6, vcc, s5, v4
	s_mov_b32 s5, 0x13000
	s_nop 0
	v_addc_co_u32_e32 v7, vcc, 0, v5, vcc
	v_mov_b32_e32 v14, v103
	v_add_co_u32_e32 v6, vcc, s5, v4
	s_mov_b32 s5, 0x17000
	s_nop 0
	v_addc_co_u32_e32 v7, vcc, 0, v5, vcc
	v_mov_b32_e32 v15, v104
	v_add_co_u32_e32 v6, vcc, s5, v4
	s_mov_b32 s5, 0x1f000
	s_nop 0
	v_addc_co_u32_e32 v7, vcc, 0, v5, vcc
	v_mov_b32_e32 v16, v105
	v_add_co_u32_e32 v6, vcc, s75, v4
	s_add_i32 s86, s86, s92
	s_nop 0
	v_addc_co_u32_e32 v7, vcc, 0, v5, vcc
	v_mov_b32_e32 v17, v106
	v_add_co_u32_e32 v6, vcc, s5, v4
	s_mov_b32 s5, 0x23000
	s_nop 0
	v_addc_co_u32_e32 v7, vcc, 0, v5, vcc
	v_mov_b32_e32 v26, v107
	s_add_i32 s4, s4, s71
	s_cmpk_gt_i32 s86, 0xff
	v_and_b32_e32 v6, 0xffff, v0
	v_lshrrev_b32_e32 v0, 16, v0
	v_and_or_b32 v12, v11, s33, v0
	v_lshl_or_b32 v6, v11, 16, v6
	v_lshrrev_b32_e32 v0, 16, v13
	v_and_b32_e32 v7, 0xffff, v13
	v_and_or_b32 v13, v14, s33, v0
	v_lshl_or_b32 v7, v14, 16, v7
	v_and_b32_e32 v8, 0xffff, v15
	v_lshrrev_b32_e32 v0, 16, v15
	v_lshl_or_b32 v8, v16, 16, v8
	v_and_or_b32 v14, v16, s33, v0
	v_and_b32_e32 v9, 0xffff, v17
	v_lshrrev_b32_e32 v0, 16, v17
	v_lshl_or_b32 v9, v26, 16, v9
	v_and_or_b32 v15, v26, s33, v0
	global_store_dwordx4 v[2:3], v[6:9], off
	global_store_dwordx4 v[2:3], v[12:15], off offset:2048
	s_nop 1
	s_nop 0
	v_add_co_u32_e32 v6, vcc, s5, v4
	s_mov_b32 s5, 0x27000
	s_nop 0
	v_addc_co_u32_e32 v7, vcc, 0, v5, vcc
	s_waitcnt vmcnt(50)
; PH_FN ph_m2a(const Params& prm, unsigned char* lds, int l_) {
;     ...
;             for (int t8 = 0; t8 < 8; ++t8) { unsigned u[8];
; #pragma unroll
;                 for (int ti = 0; ti < 8; ++ti) u[ti] = *(const unsigned*)(src + (size_t)(t8 * 8 + ti) * LDP);
;                 u32x4 lo, hi2;
;                 lo.x = (u[0] & 0xffffu) | (u[1] << 16); lo.y = (u[2] & 0xffffu) | (u[3] << 16); lo.z = (u[4] & 0xffffu) | (u[5] << 16); lo.w = (u[6] & 0xffffu) | (u[7] << 16);
;                 hi2.x = (u[0] >> 16) | (u[1] & 0xffff0000u); hi2.y = (u[2] >> 16) | (u[3] & 0xffff0000u); hi2.z = (u[4] >> 16) | (u[5] & 0xffff0000u); hi2.w = (u[6] >> 16) | (u[7] & 0xffff0000u);
;                 *(u32x4*)(d0 + (size_t)t8 * 256 * 8) = lo; *(u32x4*)(d0 + (size_t)t8 * 256 * 8 + 128 * 8) = hi2; }
	v_mov_b32_e32 v0, v108
	v_add_co_u32_e32 v6, vcc, s5, v4
	s_mov_b32 s5, 0x2b000
	s_nop 0
	v_addc_co_u32_e32 v7, vcc, 0, v5, vcc
	v_mov_b32_e32 v8, v109
	v_add_co_u32_e32 v6, vcc, s5, v4
	s_mov_b32 s5, 0x2f000
	s_nop 0
	v_addc_co_u32_e32 v7, vcc, 0, v5, vcc
	v_mov_b32_e32 v9, v110
	v_add_co_u32_e32 v6, vcc, s5, v4
	s_mov_b32 s5, 0x33000
	s_nop 0
	v_addc_co_u32_e32 v7, vcc, 0, v5, vcc
	v_mov_b32_e32 v11, v111
	v_add_co_u32_e32 v6, vcc, s5, v4
	s_mov_b32 s5, 0x37000
	s_nop 0
	v_addc_co_u32_e32 v7, vcc, 0, v5, vcc
	v_mov_b32_e32 v16, v112
	v_add_co_u32_e32 v6, vcc, s5, v4
	s_mov_b32 s5, 0x3b000
	s_nop 0
	v_addc_co_u32_e32 v7, vcc, 0, v5, vcc
	v_mov_b32_e32 v17, v113
	v_add_co_u32_e32 v6, vcc, s5, v4
	s_mov_b32 s5, 0x3f000
	s_nop 0
	v_addc_co_u32_e32 v7, vcc, 0, v5, vcc
	v_mov_b32_e32 v29, v114
	v_add_co_u32_e32 v6, vcc, s5, v4
	s_mov_b32 s5, 0x43000
	s_nop 0
	v_addc_co_u32_e32 v7, vcc, 0, v5, vcc
	v_mov_b32_e32 v6, v115
	v_and_b32_e32 v7, 0xffff, v0
	v_lshrrev_b32_e32 v0, 16, v0
	v_lshl_or_b32 v12, v8, 16, v7
	v_and_or_b32 v26, v8, s33, v0
	v_add_co_u32_e32 v8, vcc, s74, v2
	v_and_b32_e32 v7, 0xffff, v9
	v_lshrrev_b32_e32 v0, 16, v9
	v_addc_co_u32_e32 v9, vcc, 0, v3, vcc
	v_lshl_or_b32 v13, v11, 16, v7
	v_and_or_b32 v27, v11, s33, v0
	v_and_b32_e32 v7, 0xffff, v16
	v_lshrrev_b32_e32 v0, 16, v16
	v_lshl_or_b32 v14, v17, 16, v7
	v_and_or_b32 v28, v17, s33, v0
	v_and_b32_e32 v7, 0xffff, v29
	v_lshrrev_b32_e32 v0, 16, v29
	v_lshl_or_b32 v15, v6, 16, v7
	v_and_or_b32 v29, v6, s33, v0
	v_add_co_u32_e32 v6, vcc, s72, v2
	s_nop 1
	v_addc_co_u32_e32 v7, vcc, 0, v3, vcc
	global_store_dwordx4 v[6:7], v[12:15], off offset:-4096
	global_store_dwordx4 v[8:9], v[26:29], off offset:2048
	s_nop 1
	v_add_co_u32_e32 v8, vcc, s5, v4
	s_mov_b32 s5, 0x47000
	s_nop 0
	v_addc_co_u32_e32 v9, vcc, 0, v5, vcc
	s_waitcnt vmcnt(44)
	v_mov_b32_e32 v0, v116
	v_add_co_u32_e32 v8, vcc, s5, v4
	s_mov_b32 s5, 0x4b000
	s_nop 0
	v_addc_co_u32_e32 v9, vcc, 0, v5, vcc
	v_mov_b32_e32 v11, v117
	v_add_co_u32_e32 v8, vcc, s5, v4
	s_mov_b32 s5, 0x4f000
	s_nop 0
	v_addc_co_u32_e32 v9, vcc, 0, v5, vcc
	v_mov_b32_e32 v16, v118
	v_add_co_u32_e32 v8, vcc, s5, v4
	s_mov_b32 s5, 0x53000
	s_nop 0
	v_addc_co_u32_e32 v9, vcc, 0, v5, vcc
	v_mov_b32_e32 v17, v119
	v_add_co_u32_e32 v8, vcc, s5, v4
	s_mov_b32 s5, 0x57000
	s_nop 0
	v_addc_co_u32_e32 v9, vcc, 0, v5, vcc
	v_mov_b32_e32 v28, v120
	v_add_co_u32_e32 v8, vcc, s5, v4
	s_mov_b32 s5, 0x5b000
	s_nop 0
	v_addc_co_u32_e32 v9, vcc, 0, v5, vcc
	v_mov_b32_e32 v29, v121
	v_add_co_u32_e32 v8, vcc, s5, v4
	s_mov_b32 s5, 0x5f000
	s_nop 0
	v_addc_co_u32_e32 v9, vcc, 0, v5, vcc
	v_mov_b32_e32 v30, v122
	v_add_co_u32_e32 v8, vcc, s5, v4
	s_mov_b32 s5, 0x63000
	s_nop 0
	v_addc_co_u32_e32 v9, vcc, 0, v5, vcc
	v_mov_b32_e32 v8, v123
	v_and_b32_e32 v9, 0xffff, v0
	v_lshrrev_b32_e32 v0, 16, v0
	v_lshl_or_b32 v12, v11, 16, v9
	v_and_or_b32 v26, v11, s33, v0
	v_and_b32_e32 v9, 0xffff, v16
	v_lshrrev_b32_e32 v0, 16, v16
	v_lshl_or_b32 v13, v17, 16, v9
	v_and_or_b32 v27, v17, s33, v0
	v_and_b32_e32 v9, 0xffff, v28
	v_lshrrev_b32_e32 v0, 16, v28
	v_lshl_or_b32 v14, v29, 16, v9
	v_and_or_b32 v28, v29, s33, v0
	v_and_b32_e32 v9, 0xffff, v30
	v_lshrrev_b32_e32 v0, 16, v30
	v_lshl_or_b32 v15, v8, 16, v9
	v_and_or_b32 v29, v8, s33, v0
	global_store_dwordx4 v[6:7], v[12:15], off
	global_store_dwordx4 v[6:7], v[26:29], off offset:2048
	s_nop 1
	v_add_co_u32_e32 v6, vcc, s5, v4
	s_mov_b32 s5, 0x67000
	s_nop 0
	v_addc_co_u32_e32 v7, vcc, 0, v5, vcc
	s_waitcnt vmcnt(38)
	v_mov_b32_e32 v0, v124
	v_add_co_u32_e32 v6, vcc, s5, v4
	s_mov_b32 s5, 0x6b000
	s_nop 0
	v_addc_co_u32_e32 v7, vcc, 0, v5, vcc
	v_mov_b32_e32 v8, v125
	v_add_co_u32_e32 v6, vcc, s5, v4
	s_mov_b32 s5, 0x6f000
	s_nop 0
	v_addc_co_u32_e32 v7, vcc, 0, v5, vcc
	v_mov_b32_e32 v9, v126
	v_add_co_u32_e32 v6, vcc, s5, v4
	s_mov_b32 s5, 0x73000
	s_nop 0
	v_addc_co_u32_e32 v7, vcc, 0, v5, vcc
	v_mov_b32_e32 v11, v127
	v_add_co_u32_e32 v6, vcc, s5, v4
	s_mov_b32 s5, 0x77000
	s_nop 0
	v_addc_co_u32_e32 v7, vcc, 0, v5, vcc
	v_mov_b32_e32 v16, v128
	v_add_co_u32_e32 v6, vcc, s5, v4
	s_mov_b32 s5, 0x7b000
	s_nop 0
	v_addc_co_u32_e32 v7, vcc, 0, v5, vcc
	v_mov_b32_e32 v17, v129
	v_add_co_u32_e32 v6, vcc, s5, v4
	s_mov_b32 s5, 0x7f000
	s_nop 0
	v_addc_co_u32_e32 v7, vcc, 0, v5, vcc
	v_mov_b32_e32 v29, v130
	v_add_co_u32_e32 v6, vcc, s5, v4
	s_mov_b32 s5, 0x83000
	s_nop 0
	v_addc_co_u32_e32 v7, vcc, 0, v5, vcc
	v_mov_b32_e32 v6, v131
	v_and_b32_e32 v7, 0xffff, v0
	v_lshrrev_b32_e32 v0, 16, v0
	v_lshl_or_b32 v12, v8, 16, v7
	v_and_or_b32 v26, v8, s33, v0
	v_add_co_u32_e32 v8, vcc, s37, v2
	v_and_b32_e32 v7, 0xffff, v9
	v_lshrrev_b32_e32 v0, 16, v9
	v_addc_co_u32_e32 v9, vcc, 0, v3, vcc
	v_lshl_or_b32 v13, v11, 16, v7
	v_and_or_b32 v27, v11, s33, v0
	v_and_b32_e32 v7, 0xffff, v16
	v_lshrrev_b32_e32 v0, 16, v16
	v_lshl_or_b32 v14, v17, 16, v7
	v_and_or_b32 v28, v17, s33, v0
	v_and_b32_e32 v7, 0xffff, v29
	v_lshrrev_b32_e32 v0, 16, v29
	v_lshl_or_b32 v15, v6, 16, v7
	v_and_or_b32 v29, v6, s33, v0
	v_add_co_u32_e32 v6, vcc, s84, v2
	s_nop 1
	v_addc_co_u32_e32 v7, vcc, 0, v3, vcc
	global_store_dwordx4 v[6:7], v[12:15], off offset:-4096
	global_store_dwordx4 v[8:9], v[26:29], off offset:2048
	s_nop 1
	v_add_co_u32_e32 v8, vcc, s5, v4
	s_mov_b32 s5, 0x87000
	s_nop 0
	v_addc_co_u32_e32 v9, vcc, 0, v5, vcc
	s_waitcnt vmcnt(32)
; PH_FN ph_m2a(const Params& prm, unsigned char* lds, int l_) {
;     ...
;             for (int t8 = 0; t8 < 8; ++t8) { unsigned u[8];
; #pragma unroll
;                 for (int ti = 0; ti < 8; ++ti) u[ti] = *(const unsigned*)(src + (size_t)(t8 * 8 + ti) * LDP);
;                 u32x4 lo, hi2;
;                 lo.x = (u[0] & 0xffffu) | (u[1] << 16); lo.y = (u[2] & 0xffffu) | (u[3] << 16); lo.z = (u[4] & 0xffffu) | (u[5] << 16); lo.w = (u[6] & 0xffffu) | (u[7] << 16);
;                 hi2.x = (u[0] >> 16) | (u[1] & 0xffff0000u); hi2.y = (u[2] >> 16) | (u[3] & 0xffff0000u); hi2.z = (u[4] >> 16) | (u[5] & 0xffff0000u); hi2.w = (u[6] >> 16) | (u[7] & 0xffff0000u);
;                 *(u32x4*)(d0 + (size_t)t8 * 256 * 8) = lo; *(u32x4*)(d0 + (size_t)t8 * 256 * 8 + 128 * 8) = hi2; }
	v_mov_b32_e32 v0, v132
	v_add_co_u32_e32 v8, vcc, s5, v4
	s_mov_b32 s5, 0x8b000
	s_nop 0
	v_addc_co_u32_e32 v9, vcc, 0, v5, vcc
	v_mov_b32_e32 v11, v133
	v_add_co_u32_e32 v8, vcc, s5, v4
	s_mov_b32 s5, 0x8f000
	s_nop 0
	v_addc_co_u32_e32 v9, vcc, 0, v5, vcc
	v_mov_b32_e32 v16, v134
	v_add_co_u32_e32 v8, vcc, s5, v4
	s_mov_b32 s5, 0x93000
	s_nop 0
	v_addc_co_u32_e32 v9, vcc, 0, v5, vcc
	v_mov_b32_e32 v17, v135
	v_add_co_u32_e32 v8, vcc, s5, v4
	s_mov_b32 s5, 0x97000
	s_nop 0
	v_addc_co_u32_e32 v9, vcc, 0, v5, vcc
	v_mov_b32_e32 v28, v136
	v_add_co_u32_e32 v8, vcc, s5, v4
	s_mov_b32 s5, 0x9b000
	s_nop 0
	v_addc_co_u32_e32 v9, vcc, 0, v5, vcc
	v_mov_b32_e32 v29, v137
	v_add_co_u32_e32 v8, vcc, s5, v4
	s_mov_b32 s5, 0x9f000
	s_nop 0
	v_addc_co_u32_e32 v9, vcc, 0, v5, vcc
	v_mov_b32_e32 v30, v138
	v_add_co_u32_e32 v8, vcc, s5, v4
	s_mov_b32 s5, 0xa3000
	s_nop 0
	v_addc_co_u32_e32 v9, vcc, 0, v5, vcc
	v_mov_b32_e32 v8, v139
	v_and_b32_e32 v9, 0xffff, v0
	v_lshrrev_b32_e32 v0, 16, v0
	v_lshl_or_b32 v12, v11, 16, v9
	v_and_or_b32 v26, v11, s33, v0
	v_and_b32_e32 v9, 0xffff, v16
	v_lshrrev_b32_e32 v0, 16, v16
	v_lshl_or_b32 v13, v17, 16, v9
	v_and_or_b32 v27, v17, s33, v0
	v_and_b32_e32 v9, 0xffff, v28
	v_lshrrev_b32_e32 v0, 16, v28
	v_lshl_or_b32 v14, v29, 16, v9
	v_and_or_b32 v28, v29, s33, v0
	v_and_b32_e32 v9, 0xffff, v30
	v_lshrrev_b32_e32 v0, 16, v30
	v_lshl_or_b32 v15, v8, 16, v9
	v_and_or_b32 v29, v8, s33, v0
	global_store_dwordx4 v[6:7], v[12:15], off
	global_store_dwordx4 v[6:7], v[26:29], off offset:2048
	s_nop 1
	v_add_co_u32_e32 v6, vcc, s5, v4
	s_mov_b32 s5, 0xa7000
	s_nop 0
	v_addc_co_u32_e32 v7, vcc, 0, v5, vcc
	s_waitcnt vmcnt(26)
	v_mov_b32_e32 v0, v140
	v_add_co_u32_e32 v6, vcc, s5, v4
	s_mov_b32 s5, 0xab000
	s_nop 0
	v_addc_co_u32_e32 v7, vcc, 0, v5, vcc
	v_mov_b32_e32 v8, v141
	v_add_co_u32_e32 v6, vcc, s5, v4
	s_mov_b32 s5, 0xaf000
	s_nop 0
	v_addc_co_u32_e32 v7, vcc, 0, v5, vcc
	v_mov_b32_e32 v9, v142
	v_add_co_u32_e32 v6, vcc, s5, v4
	s_mov_b32 s5, 0xb3000
	s_nop 0
	v_addc_co_u32_e32 v7, vcc, 0, v5, vcc
	v_mov_b32_e32 v11, v143
	v_add_co_u32_e32 v6, vcc, s5, v4
	s_mov_b32 s5, 0xb7000
	s_nop 0
	v_addc_co_u32_e32 v7, vcc, 0, v5, vcc
	v_mov_b32_e32 v16, v144
	v_add_co_u32_e32 v6, vcc, s5, v4
	s_mov_b32 s5, 0xbb000
	s_nop 0
	v_addc_co_u32_e32 v7, vcc, 0, v5, vcc
	v_mov_b32_e32 v17, v145
	v_add_co_u32_e32 v6, vcc, s5, v4
	s_mov_b32 s5, 0xbf000
	s_nop 0
	v_addc_co_u32_e32 v7, vcc, 0, v5, vcc
	v_mov_b32_e32 v29, v146
	v_add_co_u32_e32 v6, vcc, s5, v4
	s_mov_b32 s5, 0xc3000
	s_nop 0
	v_addc_co_u32_e32 v7, vcc, 0, v5, vcc
	v_mov_b32_e32 v6, v147
	v_and_b32_e32 v7, 0xffff, v0
	v_lshrrev_b32_e32 v0, 16, v0
	v_lshl_or_b32 v12, v8, 16, v7
	v_and_or_b32 v26, v8, s33, v0
	v_add_co_u32_e32 v8, vcc, s43, v2
	v_and_b32_e32 v7, 0xffff, v9
	v_lshrrev_b32_e32 v0, 16, v9
	v_addc_co_u32_e32 v9, vcc, 0, v3, vcc
	v_lshl_or_b32 v13, v11, 16, v7
	v_and_or_b32 v27, v11, s33, v0
	v_and_b32_e32 v7, 0xffff, v16
	v_lshrrev_b32_e32 v0, 16, v16
	v_lshl_or_b32 v14, v17, 16, v7
	v_and_or_b32 v28, v17, s33, v0
	v_and_b32_e32 v7, 0xffff, v29
	v_lshrrev_b32_e32 v0, 16, v29
	v_lshl_or_b32 v15, v6, 16, v7
	v_and_or_b32 v29, v6, s33, v0
	v_add_co_u32_e32 v6, vcc, s40, v2
	s_nop 1
	v_addc_co_u32_e32 v7, vcc, 0, v3, vcc
	global_store_dwordx4 v[6:7], v[12:15], off offset:-4096
	global_store_dwordx4 v[8:9], v[26:29], off offset:2048
	s_nop 1
	v_add_co_u32_e32 v8, vcc, s5, v4
	s_mov_b32 s5, 0xc7000
	s_nop 0
	v_addc_co_u32_e32 v9, vcc, 0, v5, vcc
	s_waitcnt vmcnt(20)
	v_mov_b32_e32 v0, v148
	v_add_co_u32_e32 v8, vcc, s5, v4
	s_mov_b32 s5, 0xcb000
	s_nop 0
	v_addc_co_u32_e32 v9, vcc, 0, v5, vcc
	v_mov_b32_e32 v11, v149
	v_add_co_u32_e32 v8, vcc, s5, v4
	s_mov_b32 s5, 0xcf000
	s_nop 0
	v_addc_co_u32_e32 v9, vcc, 0, v5, vcc
	v_mov_b32_e32 v16, v150
	v_add_co_u32_e32 v8, vcc, s5, v4
	s_mov_b32 s5, 0xd3000
	s_nop 0
	v_addc_co_u32_e32 v9, vcc, 0, v5, vcc
	v_mov_b32_e32 v17, v151
	v_add_co_u32_e32 v8, vcc, s5, v4
	s_mov_b32 s5, 0xd7000
	s_nop 0
	v_addc_co_u32_e32 v9, vcc, 0, v5, vcc
	v_mov_b32_e32 v28, v152
	v_add_co_u32_e32 v8, vcc, s5, v4
	s_mov_b32 s5, 0xdb000
	s_nop 0
	v_addc_co_u32_e32 v9, vcc, 0, v5, vcc
	v_mov_b32_e32 v29, v153
	v_add_co_u32_e32 v8, vcc, s5, v4
	s_mov_b32 s5, 0xdf000
	s_nop 0
	v_addc_co_u32_e32 v9, vcc, 0, v5, vcc
	v_mov_b32_e32 v30, v154
	v_add_co_u32_e32 v8, vcc, s5, v4
	s_mov_b32 s5, 0xe3000
	s_nop 0
	v_addc_co_u32_e32 v9, vcc, 0, v5, vcc
	v_mov_b32_e32 v8, v155
	v_and_b32_e32 v9, 0xffff, v0
	v_lshrrev_b32_e32 v0, 16, v0
	v_lshl_or_b32 v12, v11, 16, v9
	v_and_or_b32 v26, v11, s33, v0
	v_and_b32_e32 v9, 0xffff, v16
	v_lshrrev_b32_e32 v0, 16, v16
	v_lshl_or_b32 v13, v17, 16, v9
	v_and_or_b32 v27, v17, s33, v0
	v_and_b32_e32 v9, 0xffff, v28
	v_lshrrev_b32_e32 v0, 16, v28
	v_lshl_or_b32 v14, v29, 16, v9
	v_and_or_b32 v28, v29, s33, v0
	v_and_b32_e32 v9, 0xffff, v30
	v_lshrrev_b32_e32 v0, 16, v30
	v_lshl_or_b32 v15, v8, 16, v9
	v_and_or_b32 v29, v8, s33, v0
	global_store_dwordx4 v[6:7], v[12:15], off
	global_store_dwordx4 v[6:7], v[26:29], off offset:2048
	s_nop 1
	v_add_co_u32_e32 v6, vcc, s5, v4
	s_mov_b32 s5, 0xe7000
	s_nop 0
	v_addc_co_u32_e32 v7, vcc, 0, v5, vcc
	s_waitcnt vmcnt(14)
	v_mov_b32_e32 v0, v156
	v_add_co_u32_e32 v6, vcc, s5, v4
	s_mov_b32 s5, 0xeb000
	s_nop 0
	v_addc_co_u32_e32 v7, vcc, 0, v5, vcc
	v_mov_b32_e32 v8, v157
	v_add_co_u32_e32 v6, vcc, s5, v4
	s_mov_b32 s5, 0xef000
	s_nop 0
	v_addc_co_u32_e32 v7, vcc, 0, v5, vcc
	v_mov_b32_e32 v9, v158
	v_add_co_u32_e32 v6, vcc, s5, v4
	s_mov_b32 s5, 0xf3000
	s_nop 0
	v_addc_co_u32_e32 v7, vcc, 0, v5, vcc
	v_mov_b32_e32 v11, v159
	v_add_co_u32_e32 v6, vcc, s5, v4
	s_mov_b32 s5, 0xf7000
	s_nop 0
	v_addc_co_u32_e32 v7, vcc, 0, v5, vcc
	v_mov_b32_e32 v14, v160
	v_add_co_u32_e32 v6, vcc, s5, v4
	s_mov_b32 s5, 0xfb000
	s_nop 0
	v_addc_co_u32_e32 v7, vcc, 0, v5, vcc
	v_mov_b32_e32 v15, v161
	v_add_co_u32_e32 v6, vcc, s5, v4
	s_mov_b32 s5, 0xff000
	s_nop 0
	v_addc_co_u32_e32 v7, vcc, 0, v5, vcc
	v_add_co_u32_e32 v4, vcc, s5, v4
	v_mov_b32_e32 v16, v162
	s_nop 0
	v_addc_co_u32_e32 v5, vcc, 0, v5, vcc
	v_mov_b32_e32 v17, v163
	v_add_co_u32_e32 v2, vcc, 0x7000, v2
	v_and_b32_e32 v4, 0xffff, v0
	v_lshrrev_b32_e32 v0, 16, v0
	v_addc_co_u32_e32 v3, vcc, 0, v3, vcc
	v_and_or_b32 v12, v8, s33, v0
	v_lshl_or_b32 v4, v8, 16, v4
	v_lshrrev_b32_e32 v0, 16, v9
	v_and_b32_e32 v5, 0xffff, v9
	v_and_or_b32 v13, v11, s33, v0
	v_lshl_or_b32 v5, v11, 16, v5
	v_and_b32_e32 v6, 0xffff, v14
	v_lshrrev_b32_e32 v0, 16, v14
	v_lshl_or_b32 v6, v15, 16, v6
	v_and_or_b32 v14, v15, s33, v0
	v_and_b32_e32 v7, 0xffff, v16
	v_lshrrev_b32_e32 v0, 16, v16
	v_lshl_or_b32 v7, v17, 16, v7
	v_and_or_b32 v15, v17, s33, v0
	global_store_dwordx4 v[2:3], v[4:7], off
	global_store_dwordx4 v[2:3], v[12:15], off offset:2048
	s_nop 1
	s_cbranch_scc1 .LBB0_344

; __device__ __forceinline__ float bf2f(unsigned v) { return __uint_as_float(v << 16); }
; PH_FN ph_m2a(const Params& prm, unsigned char* lds, int l_) {
;     ...
;         for (int cp = C.tid; cp < 768; cp += NTHREADS) {
;             const int c = 2 * cp;
;             const f32x2 w0 = *(const f32x2*)(conv_w + c), w1 = *(const f32x2*)(conv_w + 1536 + c), w2 = *(const f32x2*)(conv_w + 3072 + c), w3 = *(const f32x2*)(conv_w + 4608 + c), cb = *(const f32x2*)(conv_b + c);
;             f32x2 xm3 = {0.f, 0.f}, xm2 = {0.f, 0.f}, xm1 = {0.f, 0.f};
;             const bf16_t* __restrict__ src = PROJ + (size_t)tb * LDP + XBC0 + c;
;             if (sl0 > 0) { unsigned u;
;                 u = *(const unsigned*)(src - 3 * (size_t)LDP); xm3 = (f32x2){bf2f(u & 0xffffu), bf2f(u >> 16)};
;                 u = *(const unsigned*)(src - 2 * (size_t)LDP); xm2 = (f32x2){bf2f(u & 0xffffu), bf2f(u >> 16)};
;                 u = *(const unsigned*)(src - 1 * (size_t)LDP); xm1 = (f32x2){bf2f(u & 0xffffu), bf2f(u >> 16)}; }
;             const int h = (c >> 6) & 15;
;             const bool isx = c < 1024, isb = (c >= 1024 && c < 1280);
;             const int rr = isx ? 64 : 128, r0 = isx ? ((c & 63) >> 1) : (((c - 1024) & 127) >> 1);
;             bf16_t* __restrict__ d0 = (isx ? XT + (size_t)(b * 16 + h) * 64 * SEQ : BTS + (size_t)(b * 2 + ((c - 1024) >> 7)) * 128 * SEQ) + ((size_t)(sl0 >> 3) * rr + r0) * 8;
.LBB0_304:
	v_cmp_gt_i32_e32 vcc, s41, v69
	v_cmp_lt_i32_e64 s[22:23], s36, v69
	s_and_saveexec_b64 s[8:9], s[22:23]
	s_xor_b64 s[8:9], exec, s[8:9]
	v_add_u32_e32 v0, 0xfffffc00, v2
	v_lshrrev_b32_e32 v0, 7, v0
	v_add_u32_e32 v4, s5, v0
	s_or_saveexec_b64 s[8:9], s[8:9]
	v_mov_b64_e32 v[8:9], 7
	v_mov_b32_e32 v70, 7
	v_mov_b64_e32 v[6:7], 0x200
	v_mov_b64_e32 v[14:15], 0x8964000
	v_mov_b64_e32 v[16:17], 20
	s_xor_b64 exec, exec, s[8:9]
	v_lshrrev_b32_e32 v0, 5, v69
	v_and_or_b32 v4, v0, 15, s93
	v_mov_b64_e32 v[8:9], 6
	v_mov_b32_e32 v70, 6
	v_mov_b64_e32 v[6:7], 0x100
	v_mov_b64_e32 v[14:15], 0x1964000
	v_mov_b64_e32 v[16:17], 19
	s_or_b64 exec, exec, s[8:9]
	v_lshrrev_b32_e32 v5, 3, v69
	v_and_b32_e32 v5, 60, v5
	v_add_u32_e32 v71, 16, v5
	v_ashrrev_i32_e32 v5, 31, v4
	v_cndmask_b32_e64 v0, 63, 31, vcc
	v_lshl_add_u64 v[14:15], s[26:27], 0, v[14:15]
	v_lshlrev_b64 v[4:5], v16, v[4:5]
	v_lshlrev_b64 v[8:9], v8, s[64:65]
	v_ashrrev_i32_e32 v13, 31, v12
	v_lshl_add_u64 v[4:5], v[14:15], 0, v[4:5]
	v_and_or_b32 v8, v0, v69, v8
	v_lshlrev_b64 v[2:3], 1, v[2:3]
	s_movk_i32 s8, 0x280
	v_lshl_add_u64 v[36:37], v[12:13], 1, s[84:85]
	v_lshl_add_u64 v[38:39], v[8:9], 4, v[4:5]
	v_lshl_add_u64 v[40:41], s[76:77], 0, v[2:3]
	v_lshl_add_u64 v[42:43], s[26:27], 0, v[2:3]
	v_cmp_gt_i32_e64 s[24:25], s8, v69
	s_mov_b32 s53, 0
	s_mov_b64 s[30:31], 0
	v_lshlrev_b32_e32 v14, 1, v6
	s_mov_b32 s56, s4
	v_lshl_add_u64 v[44:45], v[36:37], 0, s[30:31]
	v_add_co_u32_e32 v74, vcc, 0x9964000, v44
	s_nop 1
	v_addc_co_u32_e32 v75, vcc, 0, v45, vcc
	global_load_dword v80, v[74:75], off offset:2048
	v_add_co_u32_e32 v74, vcc, 0x9968000, v44
	s_nop 1
	v_addc_co_u32_e32 v75, vcc, 0, v45, vcc
	global_load_dword v81, v[74:75], off offset:2048
	v_add_co_u32_e32 v74, vcc, 0x996c000, v44
	s_nop 1
	v_addc_co_u32_e32 v75, vcc, 0, v45, vcc
	global_load_dword v82, v[74:75], off offset:2048
	v_add_co_u32_e32 v74, vcc, 0x9970000, v44
	s_nop 1
	v_addc_co_u32_e32 v75, vcc, 0, v45, vcc
	global_load_dword v83, v[74:75], off offset:2048
	v_add_co_u32_e32 v74, vcc, 0x9974000, v44
	s_nop 1
	v_addc_co_u32_e32 v75, vcc, 0, v45, vcc
	global_load_dword v84, v[74:75], off offset:2048
	v_add_co_u32_e32 v74, vcc, 0x9978000, v44
	s_nop 1
	v_addc_co_u32_e32 v75, vcc, 0, v45, vcc
	global_load_dword v85, v[74:75], off offset:2048
	v_add_co_u32_e32 v74, vcc, 0x997c000, v44
	s_nop 1
	v_addc_co_u32_e32 v75, vcc, 0, v45, vcc
	global_load_dword v86, v[74:75], off offset:2048
	v_add_co_u32_e32 v74, vcc, 0x9980000, v44
	s_nop 1
	v_addc_co_u32_e32 v75, vcc, 0, v45, vcc
	global_load_dword v87, v[74:75], off offset:2048
	s_branch .LBB0_310

; __device__ __forceinline__ float bf2f(unsigned v) { return __uint_as_float(v << 16); }
; __device__ __forceinline__ unsigned pk2(float lo, float hi) { f32x2 v = {lo, hi}; bf16x2_t b = __builtin_convertvector(v, bf16x2_t); return __builtin_bit_cast(unsigned, b); }
; __device__ __forceinline__ float siluf_(float x) { return x * sigmoidf_(x); }
; PH_FN ph_m2a(const Params& prm, unsigned char* lds, int l_) {
;     ...
;             for (int t8 = 0; t8 < 8; ++t8) {
;                 float e0[8], e1[8];
; #pragma unroll
;                 for (int ti = 0; ti < 8; ++ti) { const int tt = t8 * 8 + ti;
;                     const unsigned u = *(const unsigned*)(src + (size_t)tt * LDP); const f32x2 xc = {bf2f(u & 0xffffu), bf2f(u >> 16)};
;                     f32x2 y = cb + w0 * xm3 + w1 * xm2 + w2 * xm1 + w3 * xc; xm3 = xm2; xm2 = xm1; xm1 = xc;
;                     y.x = siluf_(y.x); y.y = siluf_(y.y);
;                     const float d = isx ? dts[tt * 16 + h] : 1.f; e0[ti] = y.x * d; e1[ti] = y.y * d;
;                     if (isx) *(unsigned*)(XS + (size_t)(tb + tt) * 1024 + c) = pk2(y.x, y.y);
;                     else *(unsigned*)(BC + (size_t)(tb + tt) * 512 + (c - 1024)) = pk2(y.x, y.y); }
.LBB0_310:
	v_lshl_add_u64 v[44:45], v[36:37], 0, s[30:31]
	s_waitcnt vmcnt(0)
	v_mov_b32_e32 v96, v80
	v_mov_b32_e32 v97, v81
	v_mov_b32_e32 v98, v82
	v_mov_b32_e32 v99, v83
	v_mov_b32_e32 v100, v84
	v_mov_b32_e32 v101, v85
	v_mov_b32_e32 v102, v86
	v_mov_b32_e32 v103, v87
	s_cmp_eq_u32 s30, 0xe0000
	s_cbranch_scc1 .Lconv_nopf
	v_add_co_u32_e32 v74, vcc, 0x9984000, v44
	s_nop 1
	v_addc_co_u32_e32 v75, vcc, 0, v45, vcc
	global_load_dword v80, v[74:75], off offset:2048
	v_add_co_u32_e32 v74, vcc, 0x9988000, v44
	s_nop 1
	v_addc_co_u32_e32 v75, vcc, 0, v45, vcc
	global_load_dword v81, v[74:75], off offset:2048
	v_add_co_u32_e32 v74, vcc, 0x998c000, v44
	s_nop 1
	v_addc_co_u32_e32 v75, vcc, 0, v45, vcc
	global_load_dword v82, v[74:75], off offset:2048
	v_add_co_u32_e32 v74, vcc, 0x9990000, v44
	s_nop 1
	v_addc_co_u32_e32 v75, vcc, 0, v45, vcc
	global_load_dword v83, v[74:75], off offset:2048
	v_add_co_u32_e32 v74, vcc, 0x9994000, v44
	s_nop 1
	v_addc_co_u32_e32 v75, vcc, 0, v45, vcc
	global_load_dword v84, v[74:75], off offset:2048
	v_add_co_u32_e32 v74, vcc, 0x9998000, v44
	s_nop 1
	v_addc_co_u32_e32 v75, vcc, 0, v45, vcc
	global_load_dword v85, v[74:75], off offset:2048
	v_add_co_u32_e32 v74, vcc, 0x999c000, v44
	s_nop 1
	v_addc_co_u32_e32 v75, vcc, 0, v45, vcc
	global_load_dword v86, v[74:75], off offset:2048
	v_add_co_u32_e32 v74, vcc, 0x99a0000, v44
	s_nop 1
	v_addc_co_u32_e32 v75, vcc, 0, v45, vcc
	global_load_dword v87, v[74:75], off offset:2048
.Lconv_nopf:
	v_add_co_u32_e32 v2, vcc, 0x9964000, v44
	s_nop 1
	v_addc_co_u32_e32 v3, vcc, 0, v45, vcc
	v_mov_b32_e32 v0, v96
	v_pk_fma_f32 v[2:3], v[26:27], v[50:51], v[34:35]
	v_lshlrev_b32_e32 v6, 16, v0
	v_pk_fma_f32 v[2:3], v[28:29], v[48:49], v[2:3]
	v_and_b32_e32 v7, 0xffff0000, v0
	v_pk_fma_f32 v[2:3], v[30:31], v[52:53], v[2:3]
	s_nop 0
	v_pk_fma_f32 v[2:3], v[32:33], v[6:7], v[2:3]
	s_nop 0
	v_mul_f32_e32 v0, 0xbfb8aa3b, v2
	v_mul_f32_e32 v4, 0xbfb8aa3b, v3
	v_exp_f32_e32 v0, v0
	v_exp_f32_e32 v4, v4
	v_add_f32_e32 v0, 1.0, v0
	v_add_f32_e32 v5, 1.0, v4
	v_rcp_f32_e32 v4, v0
	v_rcp_f32_e32 v5, v5
	s_nop 0
	v_pk_mul_f32 v[16:17], v[2:3], v[4:5]
	s_nop 0
	v_cvt_pk_bf16_f32 v0, v16, v17
	s_and_saveexec_b64 s[8:9], s[22:23]
	s_xor_b64 s[8:9], exec, s[8:9]
	s_cbranch_execz .LBB0_312
	s_ashr_i32 s57, s56, 31
	s_lshl_b64 vcc, s[56:57], 10
	v_lshl_add_u64 v[2:3], v[42:43], 0, vcc
	v_add_co_u32_e32 v2, vcc, 0x7963000, v2
	s_nop 1
	v_addc_co_u32_e32 v3, vcc, 0, v3, vcc
	global_store_dword v[2:3], v0, off offset:2048
	v_mov_b32_e32 v2, v17

; __device__ __forceinline__ float bf2f(unsigned v) { return __uint_as_float(v << 16); }
; __device__ __forceinline__ unsigned pk2(float lo, float hi) { f32x2 v = {lo, hi}; bf16x2_t b = __builtin_convertvector(v, bf16x2_t); return __builtin_bit_cast(unsigned, b); }
; __device__ __forceinline__ float siluf_(float x) { return x * sigmoidf_(x); }
; PH_FN ph_m2a(const Params& prm, unsigned char* lds, int l_) {
;     ...
;                 for (int ti = 0; ti < 8; ++ti) { const int tt = t8 * 8 + ti;
;                     const unsigned u = *(const unsigned*)(src + (size_t)tt * LDP); const f32x2 xc = {bf2f(u & 0xffffu), bf2f(u >> 16)};
;                     f32x2 y = cb + w0 * xm3 + w1 * xm2 + w2 * xm1 + w3 * xc; xm3 = xm2; xm2 = xm1; xm1 = xc;
;                     y.x = siluf_(y.x); y.y = siluf_(y.y);
;                     const float d = isx ? dts[tt * 16 + h] : 1.f; e0[ti] = y.x * d; e1[ti] = y.y * d;
;                     if (isx) *(unsigned*)(XS + (size_t)(tb + tt) * 1024 + c) = pk2(y.x, y.y);
;                     else *(unsigned*)(BC + (size_t)(tb + tt) * 512 + (c - 1024)) = pk2(y.x, y.y); }
.LBB0_314:
	s_or_b64 exec, exec, s[8:9]
	v_add_co_u32_e32 v4, vcc, 0x9968000, v44
	s_nop 1
	v_addc_co_u32_e32 v5, vcc, 0, v45, vcc
	v_mov_b32_e32 v0, v97
	v_pk_fma_f32 v[4:5], v[26:27], v[48:49], v[34:35]
	v_lshlrev_b32_e32 v50, 16, v0
	v_pk_fma_f32 v[4:5], v[28:29], v[52:53], v[4:5]
	v_and_b32_e32 v51, 0xffff0000, v0
	v_pk_fma_f32 v[4:5], v[30:31], v[6:7], v[4:5]
	s_nop 0
	v_pk_fma_f32 v[4:5], v[32:33], v[50:51], v[4:5]
	s_nop 0
	v_mul_f32_e32 v0, 0xbfb8aa3b, v4
	v_mul_f32_e32 v3, 0xbfb8aa3b, v5
	v_exp_f32_e32 v0, v0
	v_exp_f32_e32 v3, v3
	v_add_f32_e32 v0, 1.0, v0
	v_add_f32_e32 v3, 1.0, v3
	v_rcp_f32_e32 v8, v0
	v_rcp_f32_e32 v9, v3
	s_nop 0
	v_pk_mul_f32 v[8:9], v[4:5], v[8:9]
	s_nop 0
	v_cvt_pk_bf16_f32 v0, v8, v9
	s_and_saveexec_b64 s[8:9], s[22:23]
	s_xor_b64 s[8:9], exec, s[8:9]
	s_cbranch_execz .LBB0_316
	s_add_i32 vcc_lo, s56, 1
	s_ashr_i32 vcc_hi, vcc_lo, 31
	s_lshl_b64 vcc, vcc, 10
	v_lshl_add_u64 v[4:5], v[42:43], 0, vcc
	v_add_co_u32_e32 v4, vcc, 0x7963000, v4
	v_mov_b32_e32 v3, v9
	s_nop 0
	v_addc_co_u32_e32 v5, vcc, 0, v5, vcc
	global_store_dword v[4:5], v0, off offset:2048
	v_mov_b32_e32 v5, v8

; __device__ __forceinline__ float bf2f(unsigned v) { return __uint_as_float(v << 16); }
; __device__ __forceinline__ unsigned pk2(float lo, float hi) { f32x2 v = {lo, hi}; bf16x2_t b = __builtin_convertvector(v, bf16x2_t); return __builtin_bit_cast(unsigned, b); }
; __device__ __forceinline__ float siluf_(float x) { return x * sigmoidf_(x); }
; PH_FN ph_m2a(const Params& prm, unsigned char* lds, int l_) {
;     ...
;                 for (int ti = 0; ti < 8; ++ti) { const int tt = t8 * 8 + ti;
;                     const unsigned u = *(const unsigned*)(src + (size_t)tt * LDP); const f32x2 xc = {bf2f(u & 0xffffu), bf2f(u >> 16)};
;                     f32x2 y = cb + w0 * xm3 + w1 * xm2 + w2 * xm1 + w3 * xc; xm3 = xm2; xm2 = xm1; xm1 = xc;
;                     y.x = siluf_(y.x); y.y = siluf_(y.y);
;                     const float d = isx ? dts[tt * 16 + h] : 1.f; e0[ti] = y.x * d; e1[ti] = y.y * d;
;                     if (isx) *(unsigned*)(XS + (size_t)(tb + tt) * 1024 + c) = pk2(y.x, y.y);
;                     else *(unsigned*)(BC + (size_t)(tb + tt) * 512 + (c - 1024)) = pk2(y.x, y.y); }
.LBB0_318:
	s_or_b64 exec, exec, s[8:9]
	v_add_co_u32_e32 v8, vcc, 0x996c000, v44
	s_nop 1
	v_addc_co_u32_e32 v9, vcc, 0, v45, vcc
	v_mov_b32_e32 v0, v98
	v_pk_fma_f32 v[8:9], v[26:27], v[52:53], v[34:35]
	v_lshlrev_b32_e32 v56, 16, v0
	v_pk_fma_f32 v[8:9], v[28:29], v[6:7], v[8:9]
	v_and_b32_e32 v57, 0xffff0000, v0
	v_pk_fma_f32 v[8:9], v[30:31], v[50:51], v[8:9]
	s_nop 0
	v_pk_fma_f32 v[8:9], v[32:33], v[56:57], v[8:9]
	s_nop 0
	v_mul_f32_e32 v0, 0xbfb8aa3b, v8
	v_mul_f32_e32 v4, 0xbfb8aa3b, v9
	v_exp_f32_e32 v0, v0
	v_exp_f32_e32 v4, v4
	v_add_f32_e32 v0, 1.0, v0
	v_add_f32_e32 v4, 1.0, v4
	v_rcp_f32_e32 v46, v0
	v_rcp_f32_e32 v47, v4
	s_nop 0
	v_pk_mul_f32 v[46:47], v[8:9], v[46:47]
	s_nop 0
	v_cvt_pk_bf16_f32 v0, v46, v47
	s_and_saveexec_b64 s[8:9], s[22:23]
	s_xor_b64 s[8:9], exec, s[8:9]
	s_cbranch_execz .LBB0_320
	s_add_i32 vcc_lo, s56, 2
	s_ashr_i32 vcc_hi, vcc_lo, 31
	s_lshl_b64 vcc, vcc, 10
	v_lshl_add_u64 v[8:9], v[42:43], 0, vcc
	v_add_co_u32_e32 v8, vcc, 0x7963000, v8
	v_mov_b32_e32 v4, v47
	s_nop 0
	v_addc_co_u32_e32 v9, vcc, 0, v9, vcc
	global_store_dword v[8:9], v0, off offset:2048

; __device__ __forceinline__ float bf2f(unsigned v) { return __uint_as_float(v << 16); }
; __device__ __forceinline__ unsigned pk2(float lo, float hi) { f32x2 v = {lo, hi}; bf16x2_t b = __builtin_convertvector(v, bf16x2_t); return __builtin_bit_cast(unsigned, b); }
; __device__ __forceinline__ float siluf_(float x) { return x * sigmoidf_(x); }
; PH_FN ph_m2a(const Params& prm, unsigned char* lds, int l_) {
;     ...
;                 for (int ti = 0; ti < 8; ++ti) { const int tt = t8 * 8 + ti;
;                     const unsigned u = *(const unsigned*)(src + (size_t)tt * LDP); const f32x2 xc = {bf2f(u & 0xffffu), bf2f(u >> 16)};
;                     f32x2 y = cb + w0 * xm3 + w1 * xm2 + w2 * xm1 + w3 * xc; xm3 = xm2; xm2 = xm1; xm1 = xc;
;                     y.x = siluf_(y.x); y.y = siluf_(y.y);
;                     const float d = isx ? dts[tt * 16 + h] : 1.f; e0[ti] = y.x * d; e1[ti] = y.y * d;
;                     if (isx) *(unsigned*)(XS + (size_t)(tb + tt) * 1024 + c) = pk2(y.x, y.y);
;                     else *(unsigned*)(BC + (size_t)(tb + tt) * 512 + (c - 1024)) = pk2(y.x, y.y); }
.LBB0_322:
	s_or_b64 exec, exec, s[8:9]
	v_add_co_u32_e32 v8, vcc, 0x9970000, v44
	v_pk_fma_f32 v[6:7], v[26:27], v[6:7], v[34:35]
	s_nop 0
	v_addc_co_u32_e32 v9, vcc, 0, v45, vcc
	v_mov_b32_e32 v0, v99
	v_pk_fma_f32 v[6:7], v[28:29], v[50:51], v[6:7]
	v_lshlrev_b32_e32 v48, 16, v0
	v_pk_fma_f32 v[6:7], v[30:31], v[56:57], v[6:7]
	v_and_b32_e32 v49, 0xffff0000, v0
	v_pk_fma_f32 v[6:7], v[32:33], v[48:49], v[6:7]
	s_nop 0
	v_mul_f32_e32 v0, 0xbfb8aa3b, v6
	v_mul_f32_e32 v8, 0xbfb8aa3b, v7
	v_exp_f32_e32 v0, v0
	v_exp_f32_e32 v8, v8
	v_add_f32_e32 v0, 1.0, v0
	v_add_f32_e32 v9, 1.0, v8
	v_rcp_f32_e32 v8, v0
	v_rcp_f32_e32 v9, v9
	s_nop 0
	v_pk_mul_f32 v[52:53], v[6:7], v[8:9]
	s_nop 0
	v_cvt_pk_bf16_f32 v0, v52, v53
	s_and_saveexec_b64 s[8:9], s[22:23]
	s_xor_b64 s[8:9], exec, s[8:9]
	s_cbranch_execz .LBB0_324
	s_add_i32 vcc_lo, s56, 3
	s_ashr_i32 vcc_hi, vcc_lo, 31
	s_lshl_b64 vcc, vcc, 10
	v_lshl_add_u64 v[6:7], v[42:43], 0, vcc
	v_add_co_u32_e32 v6, vcc, 0x7963000, v6
	v_mov_b32_e32 v9, v52
	s_nop 0
	v_addc_co_u32_e32 v7, vcc, 0, v7, vcc
	global_store_dword v[6:7], v0, off offset:2048
	v_mov_b32_e32 v7, v53

; __device__ __forceinline__ float bf2f(unsigned v) { return __uint_as_float(v << 16); }
; __device__ __forceinline__ unsigned pk2(float lo, float hi) { f32x2 v = {lo, hi}; bf16x2_t b = __builtin_convertvector(v, bf16x2_t); return __builtin_bit_cast(unsigned, b); }
; __device__ __forceinline__ float siluf_(float x) { return x * sigmoidf_(x); }
; PH_FN ph_m2a(const Params& prm, unsigned char* lds, int l_) {
;     ...
;                 for (int ti = 0; ti < 8; ++ti) { const int tt = t8 * 8 + ti;
;                     const unsigned u = *(const unsigned*)(src + (size_t)tt * LDP); const f32x2 xc = {bf2f(u & 0xffffu), bf2f(u >> 16)};
;                     f32x2 y = cb + w0 * xm3 + w1 * xm2 + w2 * xm1 + w3 * xc; xm3 = xm2; xm2 = xm1; xm1 = xc;
;                     y.x = siluf_(y.x); y.y = siluf_(y.y);
;                     const float d = isx ? dts[tt * 16 + h] : 1.f; e0[ti] = y.x * d; e1[ti] = y.y * d;
;                     if (isx) *(unsigned*)(XS + (size_t)(tb + tt) * 1024 + c) = pk2(y.x, y.y);
;                     else *(unsigned*)(BC + (size_t)(tb + tt) * 512 + (c - 1024)) = pk2(y.x, y.y); }
.LBB0_326:
	s_or_b64 exec, exec, s[8:9]
	v_add_co_u32_e32 v52, vcc, 0x9974000, v44
	v_pk_fma_f32 v[50:51], v[26:27], v[50:51], v[34:35]
	s_nop 0
	v_addc_co_u32_e32 v53, vcc, 0, v45, vcc
	v_mov_b32_e32 v0, v100
	v_pk_fma_f32 v[50:51], v[28:29], v[56:57], v[50:51]
	v_lshlrev_b32_e32 v52, 16, v0
	v_pk_fma_f32 v[50:51], v[30:31], v[48:49], v[50:51]
	v_and_b32_e32 v53, 0xffff0000, v0
	v_pk_fma_f32 v[50:51], v[32:33], v[52:53], v[50:51]
	s_nop 0
	v_mul_f32_e32 v0, 0xbfb8aa3b, v50
	v_mul_f32_e32 v6, 0xbfb8aa3b, v51
	v_exp_f32_e32 v0, v0
	v_exp_f32_e32 v6, v6
	v_add_f32_e32 v0, 1.0, v0
	v_add_f32_e32 v6, 1.0, v6
	v_rcp_f32_e32 v54, v0
	v_rcp_f32_e32 v55, v6
	s_nop 0
	v_pk_mul_f32 v[54:55], v[50:51], v[54:55]
	s_nop 0
	v_cvt_pk_bf16_f32 v0, v54, v55
	s_and_saveexec_b64 s[8:9], s[22:23]
	s_xor_b64 s[8:9], exec, s[8:9]
	s_cbranch_execz .LBB0_328
	s_add_i32 vcc_lo, s56, 4
	s_ashr_i32 vcc_hi, vcc_lo, 31
	s_lshl_b64 vcc, vcc, 10
	v_lshl_add_u64 v[50:51], v[42:43], 0, vcc
	v_add_co_u32_e32 v50, vcc, 0x7963000, v50
	v_mov_b32_e32 v6, v55
	s_nop 0
	v_addc_co_u32_e32 v51, vcc, 0, v51, vcc
	global_store_dword v[50:51], v0, off offset:2048

; __device__ __forceinline__ float bf2f(unsigned v) { return __uint_as_float(v << 16); }
; __device__ __forceinline__ unsigned pk2(float lo, float hi) { f32x2 v = {lo, hi}; bf16x2_t b = __builtin_convertvector(v, bf16x2_t); return __builtin_bit_cast(unsigned, b); }
; __device__ __forceinline__ float siluf_(float x) { return x * sigmoidf_(x); }
; PH_FN ph_m2a(const Params& prm, unsigned char* lds, int l_) {
;     ...
;                 for (int ti = 0; ti < 8; ++ti) { const int tt = t8 * 8 + ti;
;                     const unsigned u = *(const unsigned*)(src + (size_t)tt * LDP); const f32x2 xc = {bf2f(u & 0xffffu), bf2f(u >> 16)};
;                     f32x2 y = cb + w0 * xm3 + w1 * xm2 + w2 * xm1 + w3 * xc; xm3 = xm2; xm2 = xm1; xm1 = xc;
;                     y.x = siluf_(y.x); y.y = siluf_(y.y);
;                     const float d = isx ? dts[tt * 16 + h] : 1.f; e0[ti] = y.x * d; e1[ti] = y.y * d;
;                     if (isx) *(unsigned*)(XS + (size_t)(tb + tt) * 1024 + c) = pk2(y.x, y.y);
;                     else *(unsigned*)(BC + (size_t)(tb + tt) * 512 + (c - 1024)) = pk2(y.x, y.y); }
.LBB0_330:
	s_or_b64 exec, exec, s[8:9]
	v_add_co_u32_e32 v50, vcc, 0x9978000, v44
	s_nop 1
	v_addc_co_u32_e32 v51, vcc, 0, v45, vcc
	v_mov_b32_e32 v0, v101
	v_pk_fma_f32 v[50:51], v[26:27], v[56:57], v[34:35]
	s_nop 0
	v_pk_fma_f32 v[50:51], v[28:29], v[48:49], v[50:51]
	s_nop 0
	v_pk_fma_f32 v[56:57], v[30:31], v[52:53], v[50:51]
	v_lshlrev_b32_e32 v50, 16, v0
	v_and_b32_e32 v51, 0xffff0000, v0
	v_pk_fma_f32 v[56:57], v[32:33], v[50:51], v[56:57]
	s_nop 0
	v_mul_f32_e32 v0, 0xbfb8aa3b, v56
	v_mul_f32_e32 v8, 0xbfb8aa3b, v57
	v_exp_f32_e32 v0, v0
	v_exp_f32_e32 v8, v8
	v_add_f32_e32 v0, 1.0, v0
	v_add_f32_e32 v8, 1.0, v8
	v_rcp_f32_e32 v72, v0
	v_rcp_f32_e32 v73, v8
	s_nop 0
	v_pk_mul_f32 v[56:57], v[56:57], v[72:73]
	s_nop 0
	v_cvt_pk_bf16_f32 v0, v56, v57
	s_and_saveexec_b64 s[8:9], s[22:23]
	s_xor_b64 s[8:9], exec, s[8:9]
	s_cbranch_execz .LBB0_332
	s_add_i32 vcc_lo, s56, 5
	s_ashr_i32 vcc_hi, vcc_lo, 31
	s_lshl_b64 vcc, vcc, 10
	v_lshl_add_u64 v[72:73], v[42:43], 0, vcc
	v_add_co_u32_e32 v72, vcc, 0x7963000, v72
	v_mov_b32_e32 v13, v56
	s_nop 0
	v_addc_co_u32_e32 v73, vcc, 0, v73, vcc
	v_mov_b32_e32 v11, v57
	global_store_dword v[72:73], v0, off offset:2048

; __device__ __forceinline__ float bf2f(unsigned v) { return __uint_as_float(v << 16); }
; __device__ __forceinline__ unsigned pk2(float lo, float hi) { f32x2 v = {lo, hi}; bf16x2_t b = __builtin_convertvector(v, bf16x2_t); return __builtin_bit_cast(unsigned, b); }
; __device__ __forceinline__ float siluf_(float x) { return x * sigmoidf_(x); }
; PH_FN ph_m2a(const Params& prm, unsigned char* lds, int l_) {
;     ...
;                 for (int ti = 0; ti < 8; ++ti) { const int tt = t8 * 8 + ti;
;                     const unsigned u = *(const unsigned*)(src + (size_t)tt * LDP); const f32x2 xc = {bf2f(u & 0xffffu), bf2f(u >> 16)};
;                     f32x2 y = cb + w0 * xm3 + w1 * xm2 + w2 * xm1 + w3 * xc; xm3 = xm2; xm2 = xm1; xm1 = xc;
;                     y.x = siluf_(y.x); y.y = siluf_(y.y);
;                     const float d = isx ? dts[tt * 16 + h] : 1.f; e0[ti] = y.x * d; e1[ti] = y.y * d;
;                     if (isx) *(unsigned*)(XS + (size_t)(tb + tt) * 1024 + c) = pk2(y.x, y.y);
;                     else *(unsigned*)(BC + (size_t)(tb + tt) * 512 + (c - 1024)) = pk2(y.x, y.y); }
.LBB0_334:
	s_or_b64 exec, exec, s[8:9]
	v_add_co_u32_e32 v56, vcc, 0x997c000, v44
	v_pk_fma_f32 v[48:49], v[26:27], v[48:49], v[34:35]
	s_nop 0
	v_addc_co_u32_e32 v57, vcc, 0, v45, vcc
	v_mov_b32_e32 v0, v102
	v_pk_fma_f32 v[48:49], v[28:29], v[52:53], v[48:49]
	s_nop 0
	v_pk_fma_f32 v[56:57], v[30:31], v[50:51], v[48:49]
	v_lshlrev_b32_e32 v48, 16, v0
	v_and_b32_e32 v49, 0xffff0000, v0
	v_pk_fma_f32 v[56:57], v[32:33], v[48:49], v[56:57]
	s_nop 0
	v_mul_f32_e32 v0, 0xbfb8aa3b, v56
	v_mul_f32_e32 v8, 0xbfb8aa3b, v57
	v_exp_f32_e32 v0, v0
	v_exp_f32_e32 v8, v8
	v_add_f32_e32 v0, 1.0, v0
	v_add_f32_e32 v8, 1.0, v8
	v_rcp_f32_e32 v72, v0
	v_rcp_f32_e32 v73, v8
	s_nop 0
	v_pk_mul_f32 v[56:57], v[56:57], v[72:73]
	s_nop 0
	v_cvt_pk_bf16_f32 v0, v56, v57
	s_and_saveexec_b64 s[8:9], s[22:23]
	s_xor_b64 s[8:9], exec, s[8:9]
	s_cbranch_execz .LBB0_336
	s_add_i32 vcc_lo, s56, 6
	s_ashr_i32 vcc_hi, vcc_lo, 31
	s_lshl_b64 vcc, vcc, 10
	v_lshl_add_u64 v[72:73], v[42:43], 0, vcc
	v_add_co_u32_e32 v72, vcc, 0x7963000, v72
	v_mov_b32_e32 v8, v57
	s_nop 0
	v_addc_co_u32_e32 v73, vcc, 0, v73, vcc
	global_store_dword v[72:73], v0, off offset:2048

; __device__ __forceinline__ float bf2f(unsigned v) { return __uint_as_float(v << 16); }
; __device__ __forceinline__ unsigned pk2(float lo, float hi) { f32x2 v = {lo, hi}; bf16x2_t b = __builtin_convertvector(v, bf16x2_t); return __builtin_bit_cast(unsigned, b); }
; __device__ __forceinline__ float siluf_(float x) { return x * sigmoidf_(x); }
; PH_FN ph_m2a(const Params& prm, unsigned char* lds, int l_) {
;     ...
;                 for (int ti = 0; ti < 8; ++ti) { const int tt = t8 * 8 + ti;
;                     const unsigned u = *(const unsigned*)(src + (size_t)tt * LDP); const f32x2 xc = {bf2f(u & 0xffffu), bf2f(u >> 16)};
;                     f32x2 y = cb + w0 * xm3 + w1 * xm2 + w2 * xm1 + w3 * xc; xm3 = xm2; xm2 = xm1; xm1 = xc;
;                     y.x = siluf_(y.x); y.y = siluf_(y.y);
;                     const float d = isx ? dts[tt * 16 + h] : 1.f; e0[ti] = y.x * d; e1[ti] = y.y * d;
;                     if (isx) *(unsigned*)(XS + (size_t)(tb + tt) * 1024 + c) = pk2(y.x, y.y);
;                     else *(unsigned*)(BC + (size_t)(tb + tt) * 512 + (c - 1024)) = pk2(y.x, y.y); }
.LBB0_338:
	s_or_b64 exec, exec, s[8:9]
	s_mov_b32 s8, 0x9980000
	v_add_co_u32_e32 v44, vcc, s8, v44
	s_nop 1
	v_addc_co_u32_e32 v45, vcc, 0, v45, vcc
	v_mov_b32_e32 v0, v103
	v_pk_fma_f32 v[44:45], v[26:27], v[52:53], v[34:35]
	v_lshlrev_b32_e32 v52, 16, v0
	v_pk_fma_f32 v[44:45], v[28:29], v[50:51], v[44:45]
	v_and_b32_e32 v53, 0xffff0000, v0
	v_pk_fma_f32 v[44:45], v[30:31], v[48:49], v[44:45]
	s_nop 0
	v_pk_fma_f32 v[44:45], v[32:33], v[52:53], v[44:45]
	s_nop 0
	v_mul_f32_e32 v0, 0xbfb8aa3b, v44
	v_mul_f32_e32 v15, 0xbfb8aa3b, v45
	v_exp_f32_e32 v0, v0
	v_exp_f32_e32 v15, v15
	v_add_f32_e32 v0, 1.0, v0
	v_add_f32_e32 v15, 1.0, v15
	v_rcp_f32_e32 v72, v0
	v_rcp_f32_e32 v73, v15
	s_nop 0
	v_pk_mul_f32 v[44:45], v[44:45], v[72:73]
	s_nop 0
	v_cvt_pk_bf16_f32 v0, v44, v45
	s_and_saveexec_b64 s[8:9], s[22:23]
	s_xor_b64 s[8:9], exec, s[8:9]
	s_cbranch_execz .LBB0_341
	s_add_i32 vcc_lo, s56, 7
	s_ashr_i32 vcc_hi, vcc_lo, 31
	s_lshl_b64 vcc, vcc, 10
	v_mov_b32_e32 v17, v44
	v_mov_b32_e32 v15, v45
	v_lshl_add_u64 v[44:45], v[42:43], 0, vcc
	v_add_co_u32_e32 v44, vcc, 0x7963000, v44
	s_nop 1
	v_addc_co_u32_e32 v45, vcc, 0, v45, vcc
	global_store_dword v[44:45], v0, off offset:2048
	s_andn2_saveexec_b64 s[8:9], s[8:9]
	s_cbranch_execnz .LBB0_342
